# v18 + hyena Toeplitz d-loop rotated: LDS fragments of tap offset d+1 requested behind the MFMAs of tap d, counted lgkmcnt waits
# speedup vs baseline: 1.0050x; 1.0050x over previous
.LBB0_588:
	s_or_b64 exec, exec, s[72:73]
	v_mov_b32_e32 v0, 0
	v_add_u32_e32 v33, s85, v208
	v_add_u32_e32 v35, s85, v209
	s_mov_b32 s72, s83
	v_mov_b32_e32 v105, v207
	v_mov_b32_e32 v109, v204
	v_mov_b32_e32 v110, v203
	v_mov_b32_e32 v1, v0
	v_mov_b32_e32 v2, v0
	v_mov_b32_e32 v3, v0
	v_mov_b32_e32 v4, v0
	v_mov_b32_e32 v5, v0
	v_mov_b32_e32 v6, v0
	v_mov_b32_e32 v7, v0
	v_mov_b32_e32 v8, v0
	v_mov_b32_e32 v9, v0
	v_mov_b32_e32 v10, v0
	v_mov_b32_e32 v11, v0
	v_mov_b32_e32 v12, v0
	v_mov_b32_e32 v13, v0
	v_mov_b32_e32 v14, v0
	v_mov_b32_e32 v15, v0
	v_mov_b32_e32 v16, v0
	v_mov_b32_e32 v17, v0
	v_mov_b32_e32 v18, v0
	v_mov_b32_e32 v19, v0
	v_mov_b32_e32 v20, v0
	v_mov_b32_e32 v21, v0
	v_mov_b32_e32 v22, v0
	v_mov_b32_e32 v23, v0
	v_mov_b32_e32 v24, v0
	v_mov_b32_e32 v25, v0
	v_mov_b32_e32 v26, v0
	v_mov_b32_e32 v27, v0
	v_mov_b32_e32 v28, v0
	v_mov_b32_e32 v29, v0
	v_mov_b32_e32 v30, v0
	v_mov_b32_e32 v31, v0
	v_add_u32_e32 v113, v105, v131
	v_add_u32_e32 v117, v35, v131
	v_cmp_gt_u32_e32 vcc, s82, v109
	v_add_u32_e32 v114, v33, v131
	s_nop 1
	v_cndmask_b32_e32 v117, v132, v117, vcc
	v_cmp_gt_u32_e32 vcc, s82, v110
	s_nop 1
	v_cndmask_b32_e32 v114, v132, v114, vcc
	ds_read2_b32 v[210:211], v113 offset1:1
	ds_read2_b32 v[212:213], v113 offset0:2 offset1:3
	ds_read_b128 v[218:221], v117
	ds_read_b128 v[226:229], v114
	ds_read2_b32 v[214:215], v113 offset0:8 offset1:9
	ds_read2_b32 v[216:217], v113 offset0:10 offset1:11
	ds_read_b128 v[222:225], v117 offset:32
	ds_read_b128 v[230:233], v114 offset:32
.LBB0_589:
	v_add_u32_e32 v109, -1, v109
	v_add_u32_e32 v110, -1, v110
	v_subrev_u32_e32 v105, 64, v105
	v_add_u32_e32 v33, 0xffffffb0, v33
	v_add_u32_e32 v35, 0xffffffb0, v35
	v_add_u32_e32 v113, v105, v131
	v_add_u32_e32 v117, v35, v131
	v_cmp_gt_u32_e32 vcc, s82, v109
	v_add_u32_e32 v114, v33, v131
	s_nop 1
	v_cndmask_b32_e32 v117, v132, v117, vcc
	v_cmp_gt_u32_e32 vcc, s82, v110
	s_nop 1
	v_cndmask_b32_e32 v114, v132, v114, vcc
	s_waitcnt lgkmcnt(5)
	v_mfma_f32_32x32x16_bf16 v[16:31], v[210:213], v[218:221], v[16:31]
	s_waitcnt lgkmcnt(4)
	v_mfma_f32_32x32x16_bf16 v[0:15], v[210:213], v[226:229], v[0:15]
	ds_read2_b32 v[210:211], v113 offset1:1
	ds_read2_b32 v[212:213], v113 offset0:2 offset1:3
	ds_read_b128 v[218:221], v117
	ds_read_b128 v[226:229], v114
	s_waitcnt lgkmcnt(5)
	v_mfma_f32_32x32x16_bf16 v[16:31], v[214:217], v[222:225], v[16:31]
	s_waitcnt lgkmcnt(4)
	v_mfma_f32_32x32x16_bf16 v[0:15], v[214:217], v[230:233], v[0:15]
	ds_read2_b32 v[214:215], v113 offset0:8 offset1:9
	ds_read2_b32 v[216:217], v113 offset0:10 offset1:11
	ds_read_b128 v[222:225], v117 offset:32
	ds_read_b128 v[230:233], v114 offset:32
	s_add_i32 s72, s72, -1
	s_cmp_eq_u32 s72, 0
	s_cbranch_scc0 .LBB0_589
	s_waitcnt lgkmcnt(0)
	s_waitcnt vmcnt(0)
	v_lshlrev_b32_e32 v116, 16, v116
	v_lshlrev_b32_e32 v115, 16, v115
	v_lshlrev_b32_e32 v112, 16, v112
	v_lshlrev_b32_e32 v111, 16, v111
	v_lshlrev_b32_e32 v108, 16, v108
	v_lshlrev_b32_e32 v107, 16, v107
	v_lshlrev_b32_e32 v104, 16, v104
	v_lshlrev_b32_e32 v99, 16, v99
	s_add_i32 s73, s80, s85
	v_add_u32_e32 v33, s73, v205
	ds_read_b64 v[210:211], v33
	s_add_i32 s72, s80, s84
	v_add_u32_e32 v35, s72, v205
	s_waitcnt vmcnt(3)
	v_lshlrev_b32_e32 v117, 16, v80
	s_waitcnt vmcnt(2)
	v_lshlrev_b32_e32 v113, 16, v76
	s_waitcnt lgkmcnt(0)
	v_lshlrev_b32_e32 v212, 16, v210
	v_and_b32_e32 v213, 0xffff0000, v210
	v_lshlrev_b32_e32 v210, 16, v211
	v_and_b32_e32 v211, 0xffff0000, v211
	v_pk_fma_f32 v[16:17], v[106:107], v[212:213], v[16:17] op_sel_hi:[0,1,1]
	v_pk_fma_f32 v[18:19], v[106:107], v[210:211], v[18:19] op_sel_hi:[0,1,1]
	v_cvt_pk_bf16_f32 v16, v16, v17
	v_cvt_pk_bf16_f32 v17, v18, v19
	ds_write_b64 v35, v[16:17]
	ds_read_b64 v[16:17], v33 offset:16
	s_waitcnt vmcnt(1)
	v_lshlrev_b32_e32 v109, 16, v72
	s_waitcnt vmcnt(0)
	v_lshlrev_b32_e32 v105, 16, v68
	s_mov_b64 s[74:75], 0
	s_and_b64 vcc, exec, s[70:71]
	s_waitcnt lgkmcnt(0)
	v_lshlrev_b32_e32 v18, 16, v16
	v_and_b32_e32 v19, 0xffff0000, v16
	v_pk_fma_f32 v[18:19], v[106:107], v[18:19], v[20:21] op_sel_hi:[0,1,1]
	v_cvt_pk_bf16_f32 v16, v18, v19
	v_lshlrev_b32_e32 v18, 16, v17
	v_and_b32_e32 v19, 0xffff0000, v17
	v_pk_fma_f32 v[18:19], v[106:107], v[18:19], v[22:23] op_sel_hi:[0,1,1]
	v_cvt_pk_bf16_f32 v17, v18, v19
	ds_write_b64 v35, v[16:17] offset:16
	ds_read_b64 v[16:17], v33 offset:32
	v_add_u32_e32 v20, s73, v206
	v_add_u32_e32 v22, s72, v124
	s_waitcnt lgkmcnt(0)
	v_lshlrev_b32_e32 v18, 16, v16
	v_and_b32_e32 v19, 0xffff0000, v16
	v_pk_fma_f32 v[18:19], v[106:107], v[18:19], v[24:25] op_sel_hi:[0,1,1]
	v_cvt_pk_bf16_f32 v16, v18, v19
	v_lshlrev_b32_e32 v18, 16, v17
	v_and_b32_e32 v19, 0xffff0000, v17
	v_pk_fma_f32 v[18:19], v[106:107], v[18:19], v[26:27] op_sel_hi:[0,1,1]
	v_cvt_pk_bf16_f32 v17, v18, v19
	ds_write_b64 v35, v[16:17] offset:32
	ds_read_b64 v[16:17], v33 offset:48
	s_waitcnt lgkmcnt(0)
	v_lshlrev_b32_e32 v18, 16, v16
	v_and_b32_e32 v19, 0xffff0000, v16
	v_pk_fma_f32 v[18:19], v[106:107], v[18:19], v[28:29] op_sel_hi:[0,1,1]
	v_cvt_pk_bf16_f32 v16, v18, v19
	v_lshlrev_b32_e32 v18, 16, v17
	v_and_b32_e32 v19, 0xffff0000, v17
	v_pk_fma_f32 v[18:19], v[106:107], v[18:19], v[30:31] op_sel_hi:[0,1,1]
	v_cvt_pk_bf16_f32 v17, v18, v19
	ds_write_b64 v35, v[16:17] offset:48
	ds_read_b64 v[16:17], v20
	s_waitcnt lgkmcnt(0)
	v_lshlrev_b32_e32 v18, 16, v16
	v_and_b32_e32 v19, 0xffff0000, v16
	v_lshlrev_b32_e32 v16, 16, v17
	v_and_b32_e32 v17, 0xffff0000, v17
	v_pk_fma_f32 v[0:1], v[106:107], v[18:19], v[0:1] op_sel_hi:[0,1,1]
	v_pk_fma_f32 v[2:3], v[106:107], v[16:17], v[2:3] op_sel_hi:[0,1,1]
	v_cvt_pk_bf16_f32 v0, v0, v1
	v_cvt_pk_bf16_f32 v1, v2, v3
	v_add_u32_e32 v16, s72, v206
	ds_write_b64 v16, v[0:1]
	ds_read_b64 v[0:1], v20 offset:16
	s_waitcnt lgkmcnt(0)
	v_lshlrev_b32_e32 v2, 16, v0
	v_and_b32_e32 v3, 0xffff0000, v0
	v_pk_fma_f32 v[2:3], v[106:107], v[2:3], v[4:5] op_sel_hi:[0,1,1]
	v_cvt_pk_bf16_f32 v0, v2, v3
	v_lshlrev_b32_e32 v2, 16, v1
	v_and_b32_e32 v3, 0xffff0000, v1
	v_pk_fma_f32 v[2:3], v[106:107], v[2:3], v[6:7] op_sel_hi:[0,1,1]
	v_cvt_pk_bf16_f32 v1, v2, v3
	ds_write_b64 v16, v[0:1] offset:16
	ds_read_b64 v[0:1], v20 offset:32
	v_lshlrev_b32_e32 v6, 16, v83
	v_and_b32_e32 v4, 0xffff0000, v82
	v_mov_b32_e32 v5, v6
	v_and_b32_e32 v7, 0xffff0000, v83
	s_waitcnt lgkmcnt(0)
	v_lshlrev_b32_e32 v2, 16, v0
	v_and_b32_e32 v3, 0xffff0000, v0
	v_pk_fma_f32 v[2:3], v[106:107], v[2:3], v[8:9] op_sel_hi:[0,1,1]
	v_cvt_pk_bf16_f32 v0, v2, v3
	v_lshlrev_b32_e32 v2, 16, v1
	v_and_b32_e32 v3, 0xffff0000, v1
	v_pk_fma_f32 v[2:3], v[106:107], v[2:3], v[10:11] op_sel_hi:[0,1,1]
	v_cvt_pk_bf16_f32 v1, v2, v3
	ds_write_b64 v16, v[0:1] offset:32
	ds_read_b64 v[0:1], v20 offset:48
	v_mov_b32_e32 v20, v117
	v_and_b32_e32 v11, 16, v82
	v_and_b32_e32 v10, 0xffff0000, v81
	v_mov_b32_e32 v114, v7
	s_waitcnt lgkmcnt(0)
	v_lshlrev_b32_e32 v2, 16, v0
	v_and_b32_e32 v3, 0xffff0000, v0
	v_pk_fma_f32 v[2:3], v[106:107], v[2:3], v[12:13] op_sel_hi:[0,1,1]
	v_cvt_pk_bf16_f32 v0, v2, v3
	v_lshlrev_b32_e32 v2, 16, v1
	v_and_b32_e32 v3, 0xffff0000, v1
	v_pk_fma_f32 v[2:3], v[106:107], v[2:3], v[14:15] op_sel_hi:[0,1,1]
	v_cvt_pk_bf16_f32 v1, v2, v3
	ds_write_b64 v16, v[0:1] offset:48
	s_waitcnt lgkmcnt(0)
	ds_read_b128 v[0:3], v22
	v_lshlrev_b32_e32 v13, 16, v82
	v_mov_b32_e32 v12, v10
	s_waitcnt lgkmcnt(0)
	v_lshlrev_b32_e32 v14, 16, v2
	v_and_b32_e32 v15, 0xffff0000, v2
	v_and_b32_e32 v2, 0xffff0000, v80
	v_lshlrev_b32_e32 v16, 16, v1
	v_and_b32_e32 v17, 0xffff0000, v1
	v_lshlrev_b32_e32 v18, 16, v0
	v_and_b32_e32 v19, 0xffff0000, v0
	v_pk_fma_f32 v[0:1], v[100:101], v[116:117], v[102:103] op_sel_hi:[0,1,0]
	v_mov_b32_e32 v21, v2
	v_lshlrev_b32_e32 v8, 16, v3
	v_and_b32_e32 v9, 0xffff0000, v3
	v_lshlrev_b32_e32 v3, 16, v81
	v_pk_fma_f32 v[0:1], v[98:99], v[20:21], v[0:1] op_sel_hi:[0,1,1]
	v_pk_fma_f32 v[0:1], v[34:35], v[2:3], v[0:1] op_sel_hi:[0,1,1]
	v_pk_mul_f32 v[0:1], v[0:1], v[18:19]
	v_pk_fma_f32 v[18:19], v[100:101], v[2:3], v[102:103] op_sel_hi:[0,1,0]
	v_pk_mov_b32 v[2:3], v[2:3], v[10:11] op_sel:[1,0]
	v_pk_fma_f32 v[10:11], v[100:101], v[12:13], v[102:103] op_sel_hi:[0,1,0]
	v_pk_fma_f32 v[2:3], v[98:99], v[2:3], v[18:19] op_sel_hi:[0,1,1]
	v_pk_fma_f32 v[2:3], v[34:35], v[12:13], v[2:3] op_sel_hi:[0,1,1]
	v_pk_mov_b32 v[12:13], v[12:13], v[4:5] op_sel:[1,0]
	v_pk_mul_f32 v[2:3], v[2:3], v[16:17]
	v_pk_fma_f32 v[10:11], v[98:99], v[12:13], v[10:11] op_sel_hi:[0,1,1]
	v_pk_fma_f32 v[10:11], v[34:35], v[4:5], v[10:11] op_sel_hi:[0,1,1]
	v_pk_fma_f32 v[4:5], v[100:101], v[4:5], v[102:103] op_sel_hi:[0,1,0]
	v_pk_fma_f32 v[4:5], v[98:99], v[6:7], v[4:5] op_sel_hi:[0,1,1]
	v_pk_fma_f32 v[4:5], v[34:35], v[114:115], v[4:5] op_sel_hi:[0,1,1]
	v_pk_mul_f32 v[10:11], v[10:11], v[14:15]
	v_pk_mul_f32 v[4:5], v[4:5], v[8:9]
	v_cvt_pk_bf16_f32 v0, v0, v1
	v_cvt_pk_bf16_f32 v1, v2, v3
	v_cvt_pk_bf16_f32 v2, v10, v11
	v_cvt_pk_bf16_f32 v3, v4, v5
	ds_write_b128 v22, v[0:3]
	v_add_u32_e32 v22, s72, v125
	ds_read_b128 v[0:3], v22
	v_mov_b32_e32 v20, v113
	v_and_b32_e32 v11, 16, v78
	v_and_b32_e32 v10, 0xffff0000, v77
	v_lshlrev_b32_e32 v6, 16, v79
	s_waitcnt lgkmcnt(0)
	v_lshlrev_b32_e32 v14, 16, v2
	v_and_b32_e32 v15, 0xffff0000, v2
	v_and_b32_e32 v2, 0xffff0000, v76
	v_lshlrev_b32_e32 v16, 16, v1
	v_and_b32_e32 v17, 0xffff0000, v1
	v_lshlrev_b32_e32 v18, 16, v0
	v_and_b32_e32 v19, 0xffff0000, v0
	v_pk_fma_f32 v[0:1], v[100:101], v[112:113], v[102:103] op_sel_hi:[0,1,0]
	v_mov_b32_e32 v21, v2
	v_lshlrev_b32_e32 v8, 16, v3
	v_and_b32_e32 v9, 0xffff0000, v3
	v_lshlrev_b32_e32 v3, 16, v77
	v_pk_fma_f32 v[0:1], v[98:99], v[20:21], v[0:1] op_sel_hi:[0,1,1]
	v_pk_fma_f32 v[0:1], v[34:35], v[2:3], v[0:1] op_sel_hi:[0,1,1]
	v_pk_mul_f32 v[0:1], v[0:1], v[18:19]
	v_pk_fma_f32 v[18:19], v[100:101], v[2:3], v[102:103] op_sel_hi:[0,1,0]
	v_pk_mov_b32 v[2:3], v[2:3], v[10:11] op_sel:[1,0]
	v_and_b32_e32 v4, 0xffff0000, v78
	v_mov_b32_e32 v5, v6
	v_lshlrev_b32_e32 v13, 16, v78
	v_mov_b32_e32 v12, v10
	v_pk_fma_f32 v[2:3], v[98:99], v[2:3], v[18:19] op_sel_hi:[0,1,1]
	v_pk_fma_f32 v[2:3], v[34:35], v[12:13], v[2:3] op_sel_hi:[0,1,1]
	v_pk_fma_f32 v[10:11], v[100:101], v[12:13], v[102:103] op_sel_hi:[0,1,0]
	v_pk_mov_b32 v[12:13], v[12:13], v[4:5] op_sel:[1,0]
	v_and_b32_e32 v7, 0xffff0000, v79
	v_pk_fma_f32 v[10:11], v[98:99], v[12:13], v[10:11] op_sel_hi:[0,1,1]
	v_pk_fma_f32 v[10:11], v[34:35], v[4:5], v[10:11] op_sel_hi:[0,1,1]
	v_pk_fma_f32 v[4:5], v[100:101], v[4:5], v[102:103] op_sel_hi:[0,1,0]
	v_pk_fma_f32 v[4:5], v[98:99], v[6:7], v[4:5] op_sel_hi:[0,1,1]
	v_mov_b32_e32 v110, v7
	v_pk_fma_f32 v[4:5], v[34:35], v[110:111], v[4:5] op_sel_hi:[0,1,1]
	v_pk_mul_f32 v[2:3], v[2:3], v[16:17]
	v_pk_mul_f32 v[10:11], v[10:11], v[14:15]
	v_pk_mul_f32 v[4:5], v[4:5], v[8:9]
	v_cvt_pk_bf16_f32 v0, v0, v1
	v_cvt_pk_bf16_f32 v1, v2, v3
	v_cvt_pk_bf16_f32 v2, v10, v11
	v_cvt_pk_bf16_f32 v3, v4, v5
	ds_write_b128 v22, v[0:3]
	v_add_u32_e32 v22, s72, v126
	ds_read_b128 v[0:3], v22
	v_mov_b32_e32 v20, v109
	v_and_b32_e32 v11, 16, v74
	v_and_b32_e32 v10, 0xffff0000, v73
	v_lshlrev_b32_e32 v6, 16, v75
	s_waitcnt lgkmcnt(0)
	v_lshlrev_b32_e32 v14, 16, v2
	v_and_b32_e32 v15, 0xffff0000, v2
	v_and_b32_e32 v2, 0xffff0000, v72
	v_lshlrev_b32_e32 v16, 16, v1
	v_and_b32_e32 v17, 0xffff0000, v1
	v_lshlrev_b32_e32 v18, 16, v0
	v_and_b32_e32 v19, 0xffff0000, v0
	v_pk_fma_f32 v[0:1], v[100:101], v[108:109], v[102:103] op_sel_hi:[0,1,0]
	v_mov_b32_e32 v21, v2
	v_lshlrev_b32_e32 v8, 16, v3
	v_and_b32_e32 v9, 0xffff0000, v3
	v_lshlrev_b32_e32 v3, 16, v73
	v_pk_fma_f32 v[0:1], v[98:99], v[20:21], v[0:1] op_sel_hi:[0,1,1]
	v_pk_fma_f32 v[0:1], v[34:35], v[2:3], v[0:1] op_sel_hi:[0,1,1]
	v_pk_mul_f32 v[0:1], v[0:1], v[18:19]
	v_pk_fma_f32 v[18:19], v[100:101], v[2:3], v[102:103] op_sel_hi:[0,1,0]
	v_pk_mov_b32 v[2:3], v[2:3], v[10:11] op_sel:[1,0]
	v_and_b32_e32 v4, 0xffff0000, v74
	v_mov_b32_e32 v5, v6
	v_lshlrev_b32_e32 v13, 16, v74
	v_mov_b32_e32 v12, v10
	v_pk_fma_f32 v[2:3], v[98:99], v[2:3], v[18:19] op_sel_hi:[0,1,1]
	v_pk_fma_f32 v[2:3], v[34:35], v[12:13], v[2:3] op_sel_hi:[0,1,1]
	v_pk_fma_f32 v[10:11], v[100:101], v[12:13], v[102:103] op_sel_hi:[0,1,0]
	v_pk_mov_b32 v[12:13], v[12:13], v[4:5] op_sel:[1,0]
	v_and_b32_e32 v7, 0xffff0000, v75
	v_pk_fma_f32 v[10:11], v[98:99], v[12:13], v[10:11] op_sel_hi:[0,1,1]
	v_pk_fma_f32 v[10:11], v[34:35], v[4:5], v[10:11] op_sel_hi:[0,1,1]
	v_pk_fma_f32 v[4:5], v[100:101], v[4:5], v[102:103] op_sel_hi:[0,1,0]
	v_pk_fma_f32 v[4:5], v[98:99], v[6:7], v[4:5] op_sel_hi:[0,1,1]
	v_mov_b32_e32 v106, v7
	v_pk_fma_f32 v[4:5], v[34:35], v[106:107], v[4:5] op_sel_hi:[0,1,1]
	v_pk_mul_f32 v[2:3], v[2:3], v[16:17]
	v_pk_mul_f32 v[10:11], v[10:11], v[14:15]
	v_pk_mul_f32 v[4:5], v[4:5], v[8:9]
	v_cvt_pk_bf16_f32 v0, v0, v1
	v_cvt_pk_bf16_f32 v1, v2, v3
	v_cvt_pk_bf16_f32 v2, v10, v11
	v_cvt_pk_bf16_f32 v3, v4, v5
	ds_write_b128 v22, v[0:3]
	v_add_u32_e32 v22, s72, v127
	ds_read_b128 v[0:3], v22
	v_mov_b32_e32 v20, v105
	v_and_b32_e32 v11, 16, v70
	v_and_b32_e32 v10, 0xffff0000, v69
	v_lshlrev_b32_e32 v6, 16, v71
	s_waitcnt lgkmcnt(0)
	v_lshlrev_b32_e32 v14, 16, v2
	v_and_b32_e32 v15, 0xffff0000, v2
	v_and_b32_e32 v2, 0xffff0000, v68
	v_lshlrev_b32_e32 v16, 16, v1
	v_and_b32_e32 v17, 0xffff0000, v1
	v_lshlrev_b32_e32 v18, 16, v0
	v_and_b32_e32 v19, 0xffff0000, v0
	v_pk_fma_f32 v[0:1], v[100:101], v[104:105], v[102:103] op_sel_hi:[0,1,0]
	v_mov_b32_e32 v21, v2
	v_lshlrev_b32_e32 v8, 16, v3
	v_and_b32_e32 v9, 0xffff0000, v3
	v_lshlrev_b32_e32 v3, 16, v69
	v_pk_fma_f32 v[0:1], v[98:99], v[20:21], v[0:1] op_sel_hi:[0,1,1]
	v_pk_fma_f32 v[0:1], v[34:35], v[2:3], v[0:1] op_sel_hi:[0,1,1]
	v_pk_mul_f32 v[0:1], v[0:1], v[18:19]
	v_pk_fma_f32 v[18:19], v[100:101], v[2:3], v[102:103] op_sel_hi:[0,1,0]
	v_pk_mov_b32 v[2:3], v[2:3], v[10:11] op_sel:[1,0]
	v_and_b32_e32 v4, 0xffff0000, v70
	v_mov_b32_e32 v5, v6
	v_lshlrev_b32_e32 v13, 16, v70
	v_mov_b32_e32 v12, v10
	v_pk_fma_f32 v[2:3], v[98:99], v[2:3], v[18:19] op_sel_hi:[0,1,1]
	v_pk_fma_f32 v[2:3], v[34:35], v[12:13], v[2:3] op_sel_hi:[0,1,1]
	v_pk_fma_f32 v[10:11], v[100:101], v[12:13], v[102:103] op_sel_hi:[0,1,0]
	v_pk_mov_b32 v[12:13], v[12:13], v[4:5] op_sel:[1,0]
	v_and_b32_e32 v7, 0xffff0000, v71
	v_pk_fma_f32 v[10:11], v[98:99], v[12:13], v[10:11] op_sel_hi:[0,1,1]
	v_pk_fma_f32 v[10:11], v[34:35], v[4:5], v[10:11] op_sel_hi:[0,1,1]
	v_pk_fma_f32 v[4:5], v[100:101], v[4:5], v[102:103] op_sel_hi:[0,1,0]
	v_pk_fma_f32 v[4:5], v[98:99], v[6:7], v[4:5] op_sel_hi:[0,1,1]
	v_mov_b32_e32 v98, v7
	v_pk_fma_f32 v[4:5], v[34:35], v[98:99], v[4:5] op_sel_hi:[0,1,1]
	v_pk_mul_f32 v[2:3], v[2:3], v[16:17]
	v_pk_mul_f32 v[10:11], v[10:11], v[14:15]
	v_pk_mul_f32 v[4:5], v[4:5], v[8:9]
	v_cvt_pk_bf16_f32 v0, v0, v1
	v_cvt_pk_bf16_f32 v1, v2, v3
	v_cvt_pk_bf16_f32 v2, v10, v11
	v_cvt_pk_bf16_f32 v3, v4, v5
	ds_write_b128 v22, v[0:3]
	s_waitcnt lgkmcnt(0)
	s_movk_i32 s72, 0x400
	s_cbranch_vccz .LBB0_536
	v_cmp_gt_i32_e32 vcc, s47, v123
	s_waitcnt lgkmcnt(0)
	s_barrier
	s_and_saveexec_b64 s[8:9], vcc
	s_cbranch_execz .LBB0_504
	s_lshl_b32 s10, s79, 1
	s_add_u32 s10, s76, s10
	s_addc_u32 s11, s77, 0
	s_mov_b64 s[12:13], 0
